# v193 with the phase-0 offload rebalanced across the idle slots (2560/2560/1024 items for phases 1/5/7, relieving the fullest slot)
# speedup vs baseline: 1.0027x; 1.0018x over previous
.Lp0call_1:
	v_writelane_b32 v251, s0, 0
	v_writelane_b32 v251, s1, 1
	v_writelane_b32 v251, s4, 2
	v_writelane_b32 v251, s5, 3
	v_writelane_b32 v251, s26, 4
	v_writelane_b32 v251, s27, 5
	v_writelane_b32 v251, s30, 6
	v_writelane_b32 v251, s31, 7
	v_writelane_b32 v251, s34, 8
	v_writelane_b32 v251, s35, 9
	v_writelane_b32 v251, s52, 10
	v_writelane_b32 v251, s53, 11
	v_writelane_b32 v251, s54, 12
	v_writelane_b32 v251, s55, 13
	v_writelane_b32 v251, s56, 14
	v_writelane_b32 v251, s57, 15
	v_writelane_b32 v251, s58, 16
	v_writelane_b32 v251, s59, 17
	v_writelane_b32 v251, s60, 18
	v_writelane_b32 v251, s61, 19
	v_writelane_b32 v251, s62, 20
	v_writelane_b32 v251, s63, 21
	v_writelane_b32 v251, s64, 22
	v_writelane_b32 v251, s65, 23
	v_writelane_b32 v251, s66, 24
	v_writelane_b32 v251, s67, 25
	v_writelane_b32 v251, s68, 26
	v_writelane_b32 v251, s69, 27
	v_writelane_b32 v251, s70, 28
	v_writelane_b32 v251, s71, 29
	v_writelane_b32 v251, s33, 30
	v_writelane_b32 v251, s40, 31
	v_writelane_b32 v251, s41, 32
	v_writelane_b32 v251, s42, 33
	v_writelane_b32 v251, s43, 34
	v_writelane_b32 v251, s89, 35
	v_writelane_b32 v251, vcc_lo, 36
	v_writelane_b32 v251, vcc_hi, 37
	s_nop 1
	v_readlane_b32 s0, v250, 0
	v_readlane_b32 s1, v250, 1
	s_nop 3
	s_sub_u32 s0, s0, 0x90
	s_subb_u32 s1, s1, 0
	s_load_dwordx4 s[40:43], s[0:1], 0x10
	s_lshr_b32 s89, s77, 6
	s_sub_i32 s4, s6, 0x80
	s_lshl_b32 s4, s4, 3
	s_add_i32 s4, s4, s89
	s_add_i32 s4, s4, 0x4000
	s_mov_b32 s33, 0x80
	s_mov_b32 s97, 0x4a00
	s_mov_b32 s96, 1
	s_waitcnt vmcnt(0) lgkmcnt(0)
	s_branch .Lp0_entry

.Lp0call_2:
	v_writelane_b32 v251, s0, 0
	v_writelane_b32 v251, s1, 1
	v_writelane_b32 v251, s4, 2
	v_writelane_b32 v251, s5, 3
	v_writelane_b32 v251, s26, 4
	v_writelane_b32 v251, s27, 5
	v_writelane_b32 v251, s30, 6
	v_writelane_b32 v251, s31, 7
	v_writelane_b32 v251, s34, 8
	v_writelane_b32 v251, s35, 9
	v_writelane_b32 v251, s52, 10
	v_writelane_b32 v251, s53, 11
	v_writelane_b32 v251, s54, 12
	v_writelane_b32 v251, s55, 13
	v_writelane_b32 v251, s56, 14
	v_writelane_b32 v251, s57, 15
	v_writelane_b32 v251, s58, 16
	v_writelane_b32 v251, s59, 17
	v_writelane_b32 v251, s60, 18
	v_writelane_b32 v251, s61, 19
	v_writelane_b32 v251, s62, 20
	v_writelane_b32 v251, s63, 21
	v_writelane_b32 v251, s64, 22
	v_writelane_b32 v251, s65, 23
	v_writelane_b32 v251, s66, 24
	v_writelane_b32 v251, s67, 25
	v_writelane_b32 v251, s68, 26
	v_writelane_b32 v251, s69, 27
	v_writelane_b32 v251, s70, 28
	v_writelane_b32 v251, s71, 29
	v_writelane_b32 v251, s33, 30
	v_writelane_b32 v251, s40, 31
	v_writelane_b32 v251, s41, 32
	v_writelane_b32 v251, s42, 33
	v_writelane_b32 v251, s43, 34
	v_writelane_b32 v251, s89, 35
	v_writelane_b32 v251, vcc_lo, 36
	v_writelane_b32 v251, vcc_hi, 37
	s_nop 1
	v_readlane_b32 s0, v250, 0
	v_readlane_b32 s1, v250, 1
	s_nop 3
	s_sub_u32 s0, s0, 0x90
	s_subb_u32 s1, s1, 0
	s_load_dwordx4 s[40:43], s[0:1], 0x10
	s_lshr_b32 s89, s77, 6
	s_sub_i32 s4, s6, 0x80
	s_lshl_b32 s4, s4, 3
	s_add_i32 s4, s4, s89
	s_add_i32 s4, s4, 0x4a00
	s_mov_b32 s33, 0x80
	s_mov_b32 s97, 0x5400
	s_mov_b32 s96, 2
	s_waitcnt vmcnt(0) lgkmcnt(0)
	s_branch .Lp0_entry

.Lp0call_3:
	v_writelane_b32 v251, s0, 0
	v_writelane_b32 v251, s1, 1
	v_writelane_b32 v251, s4, 2
	v_writelane_b32 v251, s5, 3
	v_writelane_b32 v251, s26, 4
	v_writelane_b32 v251, s27, 5
	v_writelane_b32 v251, s30, 6
	v_writelane_b32 v251, s31, 7
	v_writelane_b32 v251, s34, 8
	v_writelane_b32 v251, s35, 9
	v_writelane_b32 v251, s52, 10
	v_writelane_b32 v251, s53, 11
	v_writelane_b32 v251, s54, 12
	v_writelane_b32 v251, s55, 13
	v_writelane_b32 v251, s56, 14
	v_writelane_b32 v251, s57, 15
	v_writelane_b32 v251, s58, 16
	v_writelane_b32 v251, s59, 17
	v_writelane_b32 v251, s60, 18
	v_writelane_b32 v251, s61, 19
	v_writelane_b32 v251, s62, 20
	v_writelane_b32 v251, s63, 21
	v_writelane_b32 v251, s64, 22
	v_writelane_b32 v251, s65, 23
	v_writelane_b32 v251, s66, 24
	v_writelane_b32 v251, s67, 25
	v_writelane_b32 v251, s68, 26
	v_writelane_b32 v251, s69, 27
	v_writelane_b32 v251, s70, 28
	v_writelane_b32 v251, s71, 29
	v_writelane_b32 v251, s33, 30
	v_writelane_b32 v251, s40, 31
	v_writelane_b32 v251, s41, 32
	v_writelane_b32 v251, s42, 33
	v_writelane_b32 v251, s43, 34
	v_writelane_b32 v251, s89, 35
	v_writelane_b32 v251, vcc_lo, 36
	v_writelane_b32 v251, vcc_hi, 37
	s_nop 1
	v_readlane_b32 s0, v250, 0
	v_readlane_b32 s1, v250, 1
	s_nop 3
	s_sub_u32 s0, s0, 0x90
	s_subb_u32 s1, s1, 0
	s_load_dwordx4 s[40:43], s[0:1], 0x10
	s_lshr_b32 s89, s77, 6
	s_sub_i32 s4, s6, 0x80
	s_lshl_b32 s4, s4, 3
	s_add_i32 s4, s4, s89
	s_add_i32 s4, s4, 0x5400
	s_mov_b32 s33, 0x80
	s_mov_b32 s97, 0x5800
	s_mov_b32 s96, 3
	s_waitcnt vmcnt(0) lgkmcnt(0)
	s_branch .Lp0_entry
